# KIND3: vmcnt wait moved from before QK to the ds_write consumers; KIND3+KIND2: S accumulators via MFMA C=0, row-max tree as v_max3 chains
# speedup vs baseline: 1.0356x; 1.0138x over previous
.LBB0_645:
	s_ashr_i32 s20, s26, 3
	s_lshr_b32 s21, s20, 29
	s_add_i32 s21, s20, s21
	s_and_b32 s27, s26, 7
	s_ashr_i32 s23, s21, 3
	s_and_b32 s21, s21, -8
	v_mov_b32_e32 v12, v206
	s_mulk_i32 s27, 0x900
	s_sub_i32 s42, s20, s21
	s_add_i32 s40, s27, 0x100
	v_and_b32_e32 v13, 31, v12
	v_ashrrev_i32_e32 v0, 1, v12
	s_lshl_b32 s31, s42, 8
	v_and_b32_e32 v0, 0xffffffe0, v0
	v_or_b32_e32 v2, s40, v13
	s_lshl_b32 s22, s23, 7
	s_waitcnt vmcnt(20)
	v_add3_u32 v146, v2, v0, s31
	s_waitcnt lgkmcnt(0)
	v_mov_b64_e32 v[2:3], s[84:85]
	s_movk_i32 s4, 0xc00
	s_waitcnt vmcnt(17)
	v_bfe_u32 v156, v12, 5, 1
	s_lshl_b32 s20, s23, 6
	s_ashr_i32 s23, s22, 31
	v_mad_i64_i32 v[2:3], s[40:41], v146, s4, v[2:3]
	s_and_b32 s20, s20, 0xffffff80
	v_lshl_add_u64 v[2:3], s[22:23], 1, v[2:3]
	v_lshlrev_b32_e32 v0, 4, v156
	s_ashr_i32 s21, s20, 31
	v_lshl_add_u64 v[2:3], v[2:3], 0, v[0:1]
	v_ashrrev_i32_e32 v0, 31, v12
	s_mul_hi_i32 s29, s20, 0x9000
	s_mul_i32 s28, s20, 0x9000
	s_lshl_b64 s[20:21], s[20:21], 1
	v_lshrrev_b32_e32 v0, 28, v0
	s_add_u32 s20, s84, s20
	v_add_u32_e32 v14, v12, v0
	s_addc_u32 s21, s85, s21
	v_ashrrev_i32_e32 v157, 4, v14
	v_add_u32_e32 v0, s27, v157
	v_mov_b64_e32 v[4:5], s[20:21]
	v_mad_i64_i32 v[6:7], s[40:41], v0, s4, v[4:5]
	v_lshlrev_b32_e32 v0, 7, v157
	v_lshlrev_b32_e32 v8, 3, v12
	v_add_u32_e32 v15, 0x200, v12
	v_sub_u32_e32 v8, v8, v0
	v_ashrrev_i32_e32 v0, 31, v15
	v_lshrrev_b32_e32 v0, 28, v0
	v_ashrrev_i32_e32 v9, 31, v8
	v_add_u32_e32 v16, v15, v0
	v_lshlrev_b64 v[8:9], 1, v[8:9]
	v_ashrrev_i32_e32 v158, 4, v16
	v_lshl_add_u64 v[6:7], v[6:7], 0, v[8:9]
	v_add_u32_e32 v0, s27, v158
	global_load_dwordx4 v[98:101], v[6:7], off offset:2048
	v_mad_i64_i32 v[4:5], s[40:41], v0, s4, v[4:5]
	v_lshlrev_b32_e32 v0, 7, v158
	v_lshlrev_b32_e32 v6, 3, v15
	v_sub_u32_e32 v6, v6, v0
	v_ashrrev_i32_e32 v7, 31, v6
	s_add_u32 s28, s86, s28
	v_lshlrev_b64 v[6:7], 1, v[6:7]
	s_addc_u32 s29, s87, s29
	v_lshl_add_u64 v[4:5], v[4:5], 0, v[6:7]
	global_load_dwordx4 v[102:105], v[4:5], off offset:2048
	v_ashrrev_i32_e32 v17, 3, v12
	v_mov_b64_e32 v[4:5], s[28:29]
	s_mov_b32 s4, 0x9000
	s_lshl_b32 s30, s27, 1
	v_mad_i64_i32 v[10:11], s[28:29], v17, s4, v[4:5]
	s_mov_b32 s31, s52
	v_lshlrev_b32_e32 v0, 4, v12
	v_lshl_add_u64 v[10:11], v[10:11], 0, s[30:31]
	v_and_b32_e32 v0, 0x70, v0
	v_lshl_add_u64 v[148:149], v[10:11], 0, v[0:1]
	v_ashrrev_i32_e32 v10, 3, v15
	v_mad_i64_i32 v[4:5], s[28:29], v10, s4, v[4:5]
	v_lshl_add_u64 v[4:5], v[4:5], 0, s[30:31]
	v_lshl_add_u64 v[150:151], v[4:5], 0, v[0:1]
	global_load_dwordx4 v[138:141], v[148:149], off
	global_load_dwordx4 v[142:145], v[150:151], off
	global_load_dwordx4 v[106:109], v[2:3], off
	global_load_dwordx4 v[110:113], v[2:3], off offset:32
	global_load_dwordx4 v[114:117], v[2:3], off offset:64
	global_load_dwordx4 v[118:121], v[2:3], off offset:96
	global_load_dwordx4 v[122:125], v[2:3], off offset:128
	global_load_dwordx4 v[126:129], v[2:3], off offset:160
	global_load_dwordx4 v[130:133], v[2:3], off offset:192
	global_load_dwordx4 v[134:137], v[2:3], off offset:224
	v_and_b32_e32 v5, 0xffffff0, v14
	v_sub_u32_e32 v5, v12, v5
	v_lshlrev_b32_e32 v11, 8, v157
	v_bitop3_b32 v5, v5, v157, 15 bitop3:0x78
	v_lshl_add_u32 v159, v5, 4, v11
	v_and_b32_e32 v5, 0xffffff0, v16
	v_sub_u32_e32 v5, v15, v5
	v_lshlrev_b32_e32 v11, 8, v158
	v_bitop3_b32 v5, v5, v158, 15 bitop3:0x78
	s_waitcnt vmcnt(28)
	v_lshl_add_u32 v160, v5, 4, v11
	v_lshrrev_b32_e32 v11, 1, v17
	v_xor_b32_e32 v11, v11, v12
	v_lshlrev_b32_e32 v5, 7, v17
	v_lshlrev_b32_e32 v11, 4, v11
	s_movk_i32 s4, 0x70
	v_and_or_b32 v161, v11, s4, v5
	v_lshlrev_b32_e32 v5, 7, v10
	v_lshrrev_b32_e32 v10, 1, v10
	v_and_b32_e32 v2, 3, v12
	v_lshlrev_b32_e32 v3, 1, v12
	v_xor_b32_e32 v10, v10, v12
	v_and_or_b32 v2, v3, 8, v2
	v_lshrrev_b32_e32 v3, 1, v12
	v_lshlrev_b32_e32 v10, 4, v10
	v_and_b32_e32 v3, 4, v3
	v_and_or_b32 v162, v10, s4, v5
	v_mov_b32_e32 v5, 0x6000
	v_lshl_or_b32 v164, v13, 7, v5
	v_bitop3_b32 v5, v2, v156, v3 bitop3:0x36
	v_lshlrev_b32_e32 v165, 4, v5
	v_or_b32_e32 v5, 2, v156
	v_bitop3_b32 v5, v2, v5, v3 bitop3:0x36
	v_lshlrev_b32_e32 v166, 4, v5
	v_or_b32_e32 v5, 4, v156
	v_bitop3_b32 v5, v2, v5, v3 bitop3:0x36
	v_lshlrev_b32_e32 v167, 4, v5
	v_or_b32_e32 v5, 6, v156
	v_bitop3_b32 v5, v2, v5, v3 bitop3:0x36
	v_lshlrev_b32_e32 v168, 4, v5
	v_or_b32_e32 v5, 8, v156
	v_or_b32_e32 v4, v2, v3
	v_bitop3_b32 v5, v2, v5, v3 bitop3:0x36
	v_and_or_b32 v4, v12, 16, v4
	v_lshlrev_b32_e32 v169, 4, v5
	v_or_b32_e32 v5, 10, v156
	v_lshrrev_b32_e32 v0, 5, v12
	v_lshlrev_b32_e32 v163, 8, v4
	v_bfe_u32 v4, v12, 1, 3
	v_bitop3_b32 v5, v2, v5, v3 bitop3:0x36
	v_lshlrev_b32_e32 v170, 4, v5
	v_or_b32_e32 v5, 12, v156
	v_bitop3_b32 v0, v0, v4, 1 bitop3:0x6c
	v_bitop3_b32 v5, v2, v5, v3 bitop3:0x36
	v_lshlrev_b32_e32 v173, 4, v0
	v_bitop3_b32 v0, v156, v4, 2 bitop3:0x36
	v_lshlrev_b32_e32 v171, 4, v5
	v_or_b32_e32 v5, 14, v156
	v_lshlrev_b32_e32 v174, 4, v0
	v_bitop3_b32 v0, v156, v4, 4 bitop3:0x36
	v_bitop3_b32 v2, v2, v5, v3 bitop3:0x36
	v_lshlrev_b32_e32 v175, 4, v0
	v_bitop3_b32 v0, v156, v4, 6 bitop3:0x36
	v_mov_b32_e32 v14, v1
	v_mov_b32_e32 v15, v1
	v_lshl_add_u64 v[152:153], s[20:21], 0, v[8:9]
	v_lshl_add_u64 v[154:155], s[20:21], 0, v[6:7]
	v_lshlrev_b32_e32 v172, 4, v2
	v_lshlrev_b32_e32 v176, 4, v0
	v_mov_b32_e32 v0, v1
	v_mov_b32_e32 v2, v1
	v_mov_b32_e32 v3, v1
	v_mov_b32_e32 v4, v1
	v_mov_b32_e32 v5, v1
	v_mov_b32_e32 v6, v1
	v_mov_b32_e32 v7, v1
	v_mov_b32_e32 v8, v1
	v_mov_b32_e32 v9, v1
	v_mov_b32_e32 v10, v1
	v_mov_b32_e32 v11, v1
	v_mov_b32_e32 v12, v1
	v_mov_b32_e32 v13, v1
	v_mov_b64_e32 v[64:65], v[14:15]
	v_mov_b64_e32 v[48:49], v[14:15]
	v_mov_b64_e32 v[32:33], v[14:15]
	s_cmp_lt_i32 s42, 0
	v_mov_b64_e32 v[62:63], v[12:13]
	v_mov_b64_e32 v[60:61], v[10:11]
	v_mov_b64_e32 v[58:59], v[8:9]
	v_mov_b64_e32 v[56:57], v[6:7]
	v_mov_b64_e32 v[54:55], v[4:5]
	v_mov_b64_e32 v[52:53], v[2:3]
	v_mov_b64_e32 v[50:51], v[0:1]
	v_mov_b64_e32 v[46:47], v[12:13]
	v_mov_b64_e32 v[44:45], v[10:11]
	v_mov_b64_e32 v[42:43], v[8:9]
	v_mov_b64_e32 v[40:41], v[6:7]
	v_mov_b64_e32 v[38:39], v[4:5]
	v_mov_b64_e32 v[36:37], v[2:3]
	v_mov_b64_e32 v[34:35], v[0:1]
	v_mov_b64_e32 v[30:31], v[12:13]
	v_mov_b64_e32 v[28:29], v[10:11]
	v_mov_b64_e32 v[26:27], v[8:9]
	v_mov_b64_e32 v[24:25], v[6:7]
	v_mov_b64_e32 v[22:23], v[4:5]
	v_mov_b64_e32 v[20:21], v[2:3]
	v_mov_b64_e32 v[18:19], v[0:1]
	v_mov_b64_e32 v[16:17], v[14:15]
	s_mov_b32 s31, 0
	v_ashrrev_i32_e32 v147, 31, v146
	s_cselect_b32 s28, 4, 36
	s_cselect_b32 s29, -3, 1
	v_mov_b32_e32 v177, 0
	v_mov_b32_e32 v179, 0xf149f2ca
	v_mov_b64_e32 v[14:15], v[12:13]
	v_mov_b64_e32 v[12:13], v[10:11]
	v_mov_b64_e32 v[10:11], v[8:9]
	v_mov_b64_e32 v[8:9], v[6:7]
	v_mov_b64_e32 v[6:7], v[4:5]
	v_mov_b64_e32 v[4:5], v[2:3]
	v_mov_b64_e32 v[2:3], v[0:1]
	s_waitcnt vmcnt(11)
	ds_write_b128 v159, v[98:101]
	s_waitcnt vmcnt(10)
	ds_write_b128 v160, v[102:105]
	s_waitcnt vmcnt(9)
	ds_write_b128 v161, v[138:141] offset:24576
	s_waitcnt vmcnt(8)
	ds_write_b128 v162, v[142:145] offset:24576
	s_waitcnt vmcnt(0)
	s_waitcnt lgkmcnt(0)
	s_barrier

.LBB0_648:
	s_mov_b32 s66, s52
	s_mov_b32 s67, s52
	s_bitcmp1_b32 s31, 0
	s_mov_b32 s53, s52
	s_mov_b32 s54, s52
	s_mov_b32 s55, s52
	s_mov_b32 s56, s52
	s_mov_b32 s57, s52
	s_mov_b32 s58, s52
	s_mov_b32 s59, s52
	s_mov_b32 s60, s52
	s_mov_b32 s61, s52
	s_mov_b32 s62, s52
	s_mov_b32 s63, s52
	s_mov_b32 s64, s52
	s_mov_b32 s65, s52
	s_cselect_b32 s31, 0xa000, 0
	v_or_b32_e32 v0, s31, v163
	v_add_u32_e32 v178, v0, v165
	v_add_u32_e32 v204, v0, v166
	v_add_u32_e32 v205, v0, v167
	v_add_u32_e32 v208, v0, v168
	v_add_u32_e32 v209, v0, v169
	v_add_u32_e32 v210, v0, v170
	v_add_u32_e32 v211, v0, v171
	v_add_u32_e32 v0, v0, v172
	ds_read_b128 v[180:183], v178 offset:0
	ds_read_b128 v[184:187], v178 offset:8192
	ds_read_b128 v[188:191], v204 offset:0
	ds_read_b128 v[192:195], v204 offset:8192
	ds_read_b128 v[196:199], v205 offset:0
	ds_read_b128 v[200:203], v205 offset:8192
	s_waitcnt lgkmcnt(5)
	v_mfma_f32_32x32x16_bf16 v[82:97], v[180:183], v[106:109], 0
	ds_read_b128 v[180:183], v208 offset:0
	s_waitcnt lgkmcnt(5)
	v_mfma_f32_32x32x16_bf16 v[66:81], v[184:187], v[106:109], 0
	ds_read_b128 v[184:187], v208 offset:8192
	s_waitcnt lgkmcnt(5)
	v_mfma_f32_32x32x16_bf16 v[82:97], v[188:191], v[110:113], v[82:97]
	ds_read_b128 v[188:191], v209 offset:0
	s_waitcnt lgkmcnt(5)
	v_mfma_f32_32x32x16_bf16 v[66:81], v[192:195], v[110:113], v[66:81]
	ds_read_b128 v[192:195], v209 offset:8192
	s_waitcnt lgkmcnt(5)
	v_mfma_f32_32x32x16_bf16 v[82:97], v[196:199], v[114:117], v[82:97]
	ds_read_b128 v[196:199], v210 offset:0
	s_waitcnt lgkmcnt(5)
	v_mfma_f32_32x32x16_bf16 v[66:81], v[200:203], v[114:117], v[66:81]
	ds_read_b128 v[200:203], v210 offset:8192
	s_waitcnt lgkmcnt(5)
	v_mfma_f32_32x32x16_bf16 v[82:97], v[180:183], v[118:121], v[82:97]
	ds_read_b128 v[180:183], v211 offset:0
	s_waitcnt lgkmcnt(5)
	v_mfma_f32_32x32x16_bf16 v[66:81], v[184:187], v[118:121], v[66:81]
	ds_read_b128 v[184:187], v211 offset:8192
	s_waitcnt lgkmcnt(5)
	v_mfma_f32_32x32x16_bf16 v[82:97], v[188:191], v[122:125], v[82:97]
	ds_read_b128 v[188:191], v0 offset:0
	s_waitcnt lgkmcnt(5)
	v_mfma_f32_32x32x16_bf16 v[66:81], v[192:195], v[122:125], v[66:81]
	ds_read_b128 v[192:195], v0 offset:8192
	s_waitcnt lgkmcnt(5)
	v_mfma_f32_32x32x16_bf16 v[82:97], v[196:199], v[126:129], v[82:97]
	s_waitcnt lgkmcnt(4)
	v_mfma_f32_32x32x16_bf16 v[66:81], v[200:203], v[126:129], v[66:81]
	s_waitcnt lgkmcnt(3)
	v_mfma_f32_32x32x16_bf16 v[82:97], v[180:183], v[130:133], v[82:97]
	s_waitcnt lgkmcnt(2)
	v_mfma_f32_32x32x16_bf16 v[66:81], v[184:187], v[130:133], v[66:81]
	s_waitcnt lgkmcnt(1)
	v_mfma_f32_32x32x16_bf16 v[82:97], v[188:191], v[134:137], v[82:97]
	s_waitcnt lgkmcnt(0)
	v_mfma_f32_32x32x16_bf16 v[66:81], v[192:195], v[134:137], v[66:81]
	s_nop 15
	s_nop 3

	s_mov_b32 s4, 0xf149f2ca
	v_max3_f32 v0, v82, v83, s4
	v_max3_f32 v178, v84, v85, v86
	v_max3_f32 v180, v87, v88, v89
	v_max3_f32 v181, v90, v91, v92
	v_max3_f32 v0, v0, v93, v94
	v_max3_f32 v178, v178, v95, v96
	v_max3_f32 v180, v180, v97, v66
	v_max3_f32 v181, v181, v67, v68
	v_max3_f32 v0, v0, v69, v70
	v_max3_f32 v178, v178, v71, v72
	v_max3_f32 v180, v180, v73, v74
	v_max3_f32 v181, v181, v75, v76
	v_max3_f32 v0, v0, v77, v78
	v_max3_f32 v178, v178, v79, v80
	v_max3_f32 v180, v180, v81, v181
	v_max3_f32 v0, v0, v178, v180
	v_mov_b32_e32 v178, v0
	s_nop 1
	v_permlane32_swap_b32_e32 v0, v178
	v_max3_f32 v178, v179, v0, v178
	v_mul_f32_e32 v0, 0xbe0293ee, v178
	v_fmamk_f32 v82, v82, 0x3e0293ee, v0
	v_exp_f32_e32 v82, v82
	v_fmamk_f32 v83, v83, 0x3e0293ee, v0
	v_exp_f32_e32 v83, v83
	v_fmamk_f32 v84, v84, 0x3e0293ee, v0
	v_exp_f32_e32 v84, v84
	v_fmamk_f32 v85, v85, 0x3e0293ee, v0
	v_sub_f32_e32 v179, v179, v178
	v_exp_f32_e32 v85, v85
	v_fmamk_f32 v86, v86, 0x3e0293ee, v0
	v_mul_f32_e32 v182, 0x3e0293ee, v179
	v_add_f32_e32 v179, 0, v82
	v_exp_f32_e32 v86, v86
	v_fmamk_f32 v87, v87, 0x3e0293ee, v0
	v_add_f32_e32 v179, v83, v179
	v_exp_f32_e32 v87, v87
	v_fmamk_f32 v88, v88, 0x3e0293ee, v0
	v_add_f32_e32 v179, v84, v179
	v_exp_f32_e32 v88, v88
	v_fmamk_f32 v89, v89, 0x3e0293ee, v0
	v_add_f32_e32 v180, v85, v179
	v_exp_f32_e32 v179, v89
	v_add_f32_e32 v89, v86, v180
	v_add_f32_e32 v89, v87, v89
	v_add_f32_e32 v89, v88, v89
	v_add_f32_e32 v180, v179, v89
	v_fmamk_f32 v89, v90, 0x3e0293ee, v0
	v_exp_f32_e32 v89, v89
	v_fmamk_f32 v90, v91, 0x3e0293ee, v0
	v_exp_f32_e32 v90, v90
	v_fmamk_f32 v91, v92, 0x3e0293ee, v0
	v_exp_f32_e32 v91, v91
	v_fmamk_f32 v92, v93, 0x3e0293ee, v0
	v_exp_f32_e32 v92, v92
	v_add_f32_e32 v93, v89, v180
	v_add_f32_e32 v93, v90, v93
	v_add_f32_e32 v93, v91, v93
	v_add_f32_e32 v180, v92, v93
	v_fmamk_f32 v93, v94, 0x3e0293ee, v0
	v_exp_f32_e32 v93, v93
	v_fmamk_f32 v94, v95, 0x3e0293ee, v0
	v_exp_f32_e32 v94, v94
	v_fmamk_f32 v95, v96, 0x3e0293ee, v0
	v_exp_f32_e32 v95, v95
	v_fmamk_f32 v96, v97, 0x3e0293ee, v0
	v_exp_f32_e32 v97, v96
	v_add_f32_e32 v96, v93, v180
	v_add_f32_e32 v96, v94, v96
	v_add_f32_e32 v96, v95, v96
	v_fmamk_f32 v66, v66, 0x3e0293ee, v0
	v_add_f32_e32 v181, v97, v96
	v_exp_f32_e32 v96, v66
	v_fmamk_f32 v66, v67, 0x3e0293ee, v0
	v_exp_f32_e32 v180, v66
	v_fmamk_f32 v66, v68, 0x3e0293ee, v0
	v_exp_f32_e32 v68, v66
	v_fmamk_f32 v66, v69, 0x3e0293ee, v0
	v_exp_f32_e32 v69, v66
	v_fmamk_f32 v67, v70, 0x3e0293ee, v0
	v_add_f32_e32 v66, v96, v181
	v_exp_f32_e32 v70, v67
	v_fmamk_f32 v67, v71, 0x3e0293ee, v0
	v_add_f32_e32 v66, v180, v66
	v_exp_f32_e32 v71, v67
	v_fmamk_f32 v67, v72, 0x3e0293ee, v0
	v_add_f32_e32 v66, v68, v66
	v_exp_f32_e32 v72, v67
	v_fmamk_f32 v67, v73, 0x3e0293ee, v0
	v_add_f32_e32 v66, v69, v66
	v_exp_f32_e32 v181, v67
	v_fmamk_f32 v67, v74, 0x3e0293ee, v0
	v_add_f32_e32 v66, v70, v66
	v_exp_f32_e32 v73, v67
	v_fmamk_f32 v67, v75, 0x3e0293ee, v0
	v_add_f32_e32 v66, v71, v66
	v_exp_f32_e32 v74, v67
	v_fmamk_f32 v67, v76, 0x3e0293ee, v0
	v_add_f32_e32 v66, v72, v66
	v_exp_f32_e32 v75, v67
	v_fmamk_f32 v67, v77, 0x3e0293ee, v0
	v_add_f32_e32 v66, v181, v66
	v_exp_f32_e32 v76, v67
	v_fmamk_f32 v67, v78, 0x3e0293ee, v0
	v_add_f32_e32 v66, v73, v66
	v_exp_f32_e32 v77, v67
	v_fmamk_f32 v67, v79, 0x3e0293ee, v0
	v_add_f32_e32 v66, v74, v66
	v_exp_f32_e32 v78, v67
	v_fmamk_f32 v67, v80, 0x3e0293ee, v0
	v_add_f32_e32 v66, v75, v66
	v_exp_f32_e32 v79, v67
	v_fmac_f32_e32 v0, 0x3e0293ee, v81
	v_add_f32_e32 v66, v76, v66
	v_exp_f32_e32 v80, v0
	v_add_f32_e32 v0, v77, v66
	v_add_f32_e32 v0, v78, v0
	v_add_f32_e32 v0, v79, v0
	v_add_f32_e32 v66, v80, v0
	v_exp_f32_e32 v0, v182
	v_mov_b32_e32 v67, v66
	s_nop 1
	v_permlane32_swap_b32_e32 v66, v67
	v_cmp_neq_f32_e32 vcc, 1.0, v0
	s_cbranch_vccz .LBB0_650
	v_pk_mul_f32 v[64:65], v[64:65], v[0:1] op_sel_hi:[1,0]
	v_pk_mul_f32 v[62:63], v[62:63], v[0:1] op_sel_hi:[1,0]
	v_pk_mul_f32 v[60:61], v[60:61], v[0:1] op_sel_hi:[1,0]
	v_pk_mul_f32 v[58:59], v[58:59], v[0:1] op_sel_hi:[1,0]
	v_pk_mul_f32 v[56:57], v[56:57], v[0:1] op_sel_hi:[1,0]
	v_pk_mul_f32 v[54:55], v[54:55], v[0:1] op_sel_hi:[1,0]
	v_pk_mul_f32 v[52:53], v[52:53], v[0:1] op_sel_hi:[1,0]
	v_pk_mul_f32 v[50:51], v[50:51], v[0:1] op_sel_hi:[1,0]
	v_pk_mul_f32 v[48:49], v[48:49], v[0:1] op_sel_hi:[1,0]
	v_pk_mul_f32 v[46:47], v[46:47], v[0:1] op_sel_hi:[1,0]
	v_pk_mul_f32 v[44:45], v[44:45], v[0:1] op_sel_hi:[1,0]
	v_pk_mul_f32 v[42:43], v[42:43], v[0:1] op_sel_hi:[1,0]
	v_pk_mul_f32 v[40:41], v[40:41], v[0:1] op_sel_hi:[1,0]
	v_pk_mul_f32 v[38:39], v[38:39], v[0:1] op_sel_hi:[1,0]
	v_pk_mul_f32 v[36:37], v[36:37], v[0:1] op_sel_hi:[1,0]
	v_pk_mul_f32 v[34:35], v[34:35], v[0:1] op_sel_hi:[1,0]
	v_pk_mul_f32 v[32:33], v[32:33], v[0:1] op_sel_hi:[1,0]
	v_pk_mul_f32 v[30:31], v[30:31], v[0:1] op_sel_hi:[1,0]
	v_pk_mul_f32 v[28:29], v[28:29], v[0:1] op_sel_hi:[1,0]
	v_pk_mul_f32 v[26:27], v[26:27], v[0:1] op_sel_hi:[1,0]
	v_pk_mul_f32 v[24:25], v[24:25], v[0:1] op_sel_hi:[1,0]
	v_pk_mul_f32 v[22:23], v[22:23], v[0:1] op_sel_hi:[1,0]
	v_pk_mul_f32 v[20:21], v[20:21], v[0:1] op_sel_hi:[1,0]
	v_pk_mul_f32 v[18:19], v[18:19], v[0:1] op_sel_hi:[1,0]
	v_pk_mul_f32 v[16:17], v[16:17], v[0:1] op_sel_hi:[1,0]
	v_pk_mul_f32 v[14:15], v[14:15], v[0:1] op_sel_hi:[1,0]
	v_pk_mul_f32 v[12:13], v[12:13], v[0:1] op_sel_hi:[1,0]
	v_pk_mul_f32 v[10:11], v[10:11], v[0:1] op_sel_hi:[1,0]
	v_pk_mul_f32 v[8:9], v[8:9], v[0:1] op_sel_hi:[1,0]
	v_pk_mul_f32 v[6:7], v[6:7], v[0:1] op_sel_hi:[1,0]
	v_pk_mul_f32 v[4:5], v[4:5], v[0:1] op_sel_hi:[1,0]
	v_pk_mul_f32 v[2:3], v[2:3], v[0:1] op_sel_hi:[1,0]
.LBB0_650:
	v_add_u32_e32 v81, s31, v164
	v_cvt_pk_bf16_f32 v82, v82, v83
	v_cvt_pk_bf16_f32 v83, v84, v85
	v_cvt_pk_bf16_f32 v84, v86, v87
	v_cvt_pk_bf16_f32 v85, v88, v179
	v_cvt_pk_bf16_f32 v86, v89, v90
	v_cvt_pk_bf16_f32 v87, v91, v92
	v_cvt_pk_bf16_f32 v88, v93, v94
	v_cvt_pk_bf16_f32 v89, v95, v97
	v_cvt_pk_bf16_f32 v90, v96, v180
	v_cvt_pk_bf16_f32 v91, v68, v69
	v_cvt_pk_bf16_f32 v92, v70, v71
	v_cvt_pk_bf16_f32 v93, v72, v181
	v_cvt_pk_bf16_f32 v68, v73, v74
	v_cvt_pk_bf16_f32 v69, v75, v76
	v_cvt_pk_bf16_f32 v70, v77, v78
	v_cvt_pk_bf16_f32 v71, v79, v80
	v_add_u32_e32 v80, v81, v173
	v_add_u32_e32 v179, v81, v174
	v_add_u32_e32 v192, v81, v175
	v_add_u32_e32 v81, v81, v176
	ds_read_b128 v[72:75], v80 offset:0
	ds_read_b128 v[76:79], v80 offset:4096
	ds_read_b128 v[94:97], v80 offset:8192
	ds_read_b128 v[180:183], v80 offset:12288
	ds_read_b128 v[184:187], v179 offset:0
	ds_read_b128 v[188:191], v179 offset:4096
	s_waitcnt lgkmcnt(5)
	v_mfma_f32_32x32x16_bf16 v[50:65], v[72:75], v[82:85], v[50:65]
	ds_read_b128 v[72:75], v179 offset:8192
	s_waitcnt lgkmcnt(5)
	v_mfma_f32_32x32x16_bf16 v[34:49], v[76:79], v[82:85], v[34:49]
	ds_read_b128 v[76:79], v179 offset:12288
	s_waitcnt lgkmcnt(5)
	v_mfma_f32_32x32x16_bf16 v[18:33], v[94:97], v[82:85], v[18:33]
	ds_read_b128 v[94:97], v192 offset:0
	s_waitcnt lgkmcnt(5)
	v_mfma_f32_32x32x16_bf16 v[2:17], v[180:183], v[82:85], v[2:17]
	ds_read_b128 v[180:183], v192 offset:4096
	s_waitcnt lgkmcnt(5)
	v_mfma_f32_32x32x16_bf16 v[50:65], v[184:187], v[86:89], v[50:65]
	ds_read_b128 v[184:187], v192 offset:8192
	s_waitcnt lgkmcnt(5)
	v_mfma_f32_32x32x16_bf16 v[34:49], v[188:191], v[86:89], v[34:49]
	ds_read_b128 v[188:191], v192 offset:12288
	s_waitcnt lgkmcnt(5)
	v_mfma_f32_32x32x16_bf16 v[18:33], v[72:75], v[86:89], v[18:33]
	ds_read_b128 v[72:75], v81 offset:0
	s_waitcnt lgkmcnt(5)
	v_mfma_f32_32x32x16_bf16 v[2:17], v[76:79], v[86:89], v[2:17]
	ds_read_b128 v[76:79], v81 offset:4096
	s_waitcnt lgkmcnt(5)
	v_mfma_f32_32x32x16_bf16 v[50:65], v[94:97], v[90:93], v[50:65]
	ds_read_b128 v[94:97], v81 offset:8192
	s_waitcnt lgkmcnt(5)
	v_mfma_f32_32x32x16_bf16 v[34:49], v[180:183], v[90:93], v[34:49]
	ds_read_b128 v[180:183], v81 offset:12288
	s_waitcnt lgkmcnt(5)
	v_mfma_f32_32x32x16_bf16 v[18:33], v[184:187], v[90:93], v[18:33]
	s_waitcnt lgkmcnt(4)
	v_mfma_f32_32x32x16_bf16 v[2:17], v[188:191], v[90:93], v[2:17]
	s_waitcnt lgkmcnt(3)
	v_mfma_f32_32x32x16_bf16 v[50:65], v[72:75], v[68:71], v[50:65]
	s_waitcnt lgkmcnt(2)
	v_mfma_f32_32x32x16_bf16 v[34:49], v[76:79], v[68:71], v[34:49]
	s_waitcnt lgkmcnt(1)
	v_mfma_f32_32x32x16_bf16 v[18:33], v[94:97], v[68:71], v[18:33]
	s_waitcnt lgkmcnt(0)
	v_mfma_f32_32x32x16_bf16 v[2:17], v[180:183], v[68:71], v[2:17]
	s_nop 15
	s_nop 3

	s_andn2_b64 vcc, exec, s[20:21]
	s_movk_i32 s66, 0xff
	v_readlane_b32 s54, v255, 3
	v_readlane_b32 s55, v255, 4
	s_cbranch_vccnz .LBB0_652
	s_bitcmp1_b32 s30, 0
	s_cselect_b32 s20, 0xa000, 0
	v_add_u32_e32 v68, s20, v159
	v_add_u32_e32 v69, s20, v160
	v_add_u32_e32 v70, s20, v161
	v_add_u32_e32 v71, s20, v162
	s_waitcnt vmcnt(3)
	ds_write_b128 v68, v[98:101]
	s_waitcnt vmcnt(2)
	ds_write_b128 v69, v[102:105]
	s_waitcnt vmcnt(1)
	ds_write_b128 v70, v[138:141] offset:24576
	s_waitcnt vmcnt(0)
	ds_write_b128 v71, v[142:145] offset:24576

.LBB0_674:
	s_bitcmp1_b32 s31, 0
	s_cselect_b32 s31, 0xa000, 0
	v_add_u32_e32 v0, s31, v193
	v_mov_b32_e32 v14, v1
	v_mov_b32_e32 v15, v1
	v_add_u32_e32 v182, v0, v195
	v_add_u32_e32 v201, v0, v196
	v_add_u32_e32 v202, v0, v197
	v_add_u32_e32 v204, v0, v198
	v_mov_b32_e32 v0, v1
	v_mov_b32_e32 v2, v1
	v_mov_b32_e32 v3, v1
	v_mov_b32_e32 v4, v1
	v_mov_b32_e32 v5, v1
	v_mov_b32_e32 v6, v1
	v_mov_b32_e32 v7, v1
	v_mov_b32_e32 v8, v1
	v_mov_b32_e32 v9, v1
	v_mov_b32_e32 v10, v1
	v_mov_b32_e32 v11, v1
	v_mov_b32_e32 v12, v1
	v_mov_b32_e32 v13, v1
	ds_read_b128 v[214:217], v182 offset:0
	ds_read_b128 v[228:231], v201 offset:0
	ds_read_b128 v[232:235], v202 offset:0
	ds_read_b128 v[236:239], v204 offset:0
	ds_read_b128 v[240:243], v182 offset:128
	ds_read_b128 v[244:247], v201 offset:128
	s_waitcnt lgkmcnt(5)
	v_mfma_f32_32x32x16_bf16 v[80:95], v[214:217], v[96:99], 0
	ds_read_b128 v[214:217], v202 offset:128
	s_waitcnt lgkmcnt(5)
	v_mfma_f32_32x32x16_bf16 v[80:95], v[228:231], v[100:103], v[80:95]
	ds_read_b128 v[228:231], v204 offset:128
	s_waitcnt lgkmcnt(5)
	v_mfma_f32_32x32x16_bf16 v[80:95], v[232:235], v[104:107], v[80:95]
	ds_read_b128 v[232:235], v182 offset:256
	s_waitcnt lgkmcnt(5)
	v_mfma_f32_32x32x16_bf16 v[80:95], v[236:239], v[108:111], v[80:95]
	ds_read_b128 v[236:239], v201 offset:256
	s_waitcnt lgkmcnt(5)
	v_mfma_f32_32x32x16_bf16 v[80:95], v[240:243], v[112:115], v[80:95]
	ds_read_b128 v[240:243], v202 offset:256
	s_waitcnt lgkmcnt(5)
	v_mfma_f32_32x32x16_bf16 v[80:95], v[244:247], v[116:119], v[80:95]
	ds_read_b128 v[244:247], v204 offset:256
	s_waitcnt lgkmcnt(5)
	v_mfma_f32_32x32x16_bf16 v[80:95], v[214:217], v[120:123], v[80:95]
	s_waitcnt lgkmcnt(4)
	v_mfma_f32_32x32x16_bf16 v[80:95], v[228:231], v[124:127], v[80:95]
	s_waitcnt lgkmcnt(3)
	v_mfma_f32_32x32x16_bf16 v[80:95], v[232:235], v[128:131], v[80:95]
	s_waitcnt lgkmcnt(2)
	v_mfma_f32_32x32x16_bf16 v[80:95], v[236:239], v[132:135], v[80:95]
	s_waitcnt lgkmcnt(1)
	v_mfma_f32_32x32x16_bf16 v[80:95], v[240:243], v[136:139], v[80:95]
	s_waitcnt lgkmcnt(0)
	v_mfma_f32_32x32x16_bf16 v[80:95], v[244:247], v[140:143], v[80:95]
	s_nop 15
	s_nop 3

	s_mov_b32 s4, 0xf149f2ca
	v_max3_f32 v182, v80, v81, s4
	v_max3_f32 v201, v82, v83, v84
	v_max3_f32 v202, v85, v86, v87
	v_max3_f32 v182, v182, v88, v89
	v_max3_f32 v201, v201, v90, v91
	v_max3_f32 v202, v202, v92, v93
	v_max3_f32 v182, v182, v94, v95
	v_max3_f32 v182, v182, v201, v202
	v_mov_b32_e32 v201, v182
	s_nop 1
	v_permlane32_swap_b32_e32 v182, v201
	v_max3_f32 v205, v203, v182, v201
	v_mul_f32_e32 v182, 0xbdd53b94, v205
	v_fmamk_f32 v80, v80, 0x3dd53b94, v182
	v_exp_f32_e32 v80, v80
	v_fmamk_f32 v81, v81, 0x3dd53b94, v182
	v_exp_f32_e32 v81, v81
	v_fmamk_f32 v82, v82, 0x3dd53b94, v182
	v_exp_f32_e32 v82, v82
	v_fmamk_f32 v83, v83, 0x3dd53b94, v182
	v_sub_f32_e32 v201, v203, v205
	v_exp_f32_e32 v83, v83
	v_fmamk_f32 v84, v84, 0x3dd53b94, v182
	v_mul_f32_e32 v202, 0x3dd53b94, v201
	v_add_f32_e32 v201, 0, v80
	v_exp_f32_e32 v84, v84
	v_fmamk_f32 v85, v85, 0x3dd53b94, v182
	v_add_f32_e32 v201, v81, v201
	v_exp_f32_e32 v85, v85
	v_fmamk_f32 v86, v86, 0x3dd53b94, v182
	v_add_f32_e32 v201, v82, v201
	v_exp_f32_e32 v86, v86
	v_fmamk_f32 v87, v87, 0x3dd53b94, v182
	v_add_f32_e32 v201, v83, v201
	v_exp_f32_e32 v203, v87
	v_add_f32_e32 v87, v84, v201
	v_add_f32_e32 v87, v85, v87
	v_add_f32_e32 v87, v86, v87
	v_add_f32_e32 v201, v203, v87
	v_fmamk_f32 v87, v88, 0x3dd53b94, v182
	v_exp_f32_e32 v87, v87
	v_fmamk_f32 v88, v89, 0x3dd53b94, v182
	v_exp_f32_e32 v88, v88
	v_fmamk_f32 v89, v90, 0x3dd53b94, v182
	v_exp_f32_e32 v89, v89
	v_fmamk_f32 v90, v91, 0x3dd53b94, v182
	v_exp_f32_e32 v90, v90
	v_add_f32_e32 v91, v87, v201
	v_add_f32_e32 v91, v88, v91
	v_add_f32_e32 v91, v89, v91
	v_add_f32_e32 v201, v90, v91
	v_fmamk_f32 v91, v92, 0x3dd53b94, v182
	v_exp_f32_e32 v91, v91
	v_fmamk_f32 v92, v93, 0x3dd53b94, v182
	v_exp_f32_e32 v92, v92
	v_fmamk_f32 v93, v94, 0x3dd53b94, v182
	v_exp_f32_e32 v93, v93
	v_fmac_f32_e32 v182, 0x3dd53b94, v95
	v_exp_f32_e32 v94, v182
	v_add_f32_e32 v95, v91, v201
	v_add_f32_e32 v95, v92, v95
	v_exp_f32_e32 v182, v202
	v_add_f32_e32 v95, v93, v95
	v_add_f32_e32 v201, v94, v95
	v_mov_b32_e32 v202, v201
	s_nop 1
	v_permlane32_swap_b32_e32 v201, v202
	v_cmp_neq_f32_e32 vcc, 1.0, v182
	s_cbranch_vccz .LBB0_676
	v_pk_mul_f32 v[78:79], v[78:79], v[182:183] op_sel_hi:[1,0]
	v_pk_mul_f32 v[76:77], v[76:77], v[182:183] op_sel_hi:[1,0]
	v_pk_mul_f32 v[74:75], v[74:75], v[182:183] op_sel_hi:[1,0]
	v_pk_mul_f32 v[72:73], v[72:73], v[182:183] op_sel_hi:[1,0]
	v_pk_mul_f32 v[70:71], v[70:71], v[182:183] op_sel_hi:[1,0]
	v_pk_mul_f32 v[68:69], v[68:69], v[182:183] op_sel_hi:[1,0]
	v_pk_mul_f32 v[66:67], v[66:67], v[182:183] op_sel_hi:[1,0]
	v_pk_mul_f32 v[64:65], v[64:65], v[182:183] op_sel_hi:[1,0]
	v_pk_mul_f32 v[62:63], v[62:63], v[182:183] op_sel_hi:[1,0]
	v_pk_mul_f32 v[60:61], v[60:61], v[182:183] op_sel_hi:[1,0]
	v_pk_mul_f32 v[58:59], v[58:59], v[182:183] op_sel_hi:[1,0]
	v_pk_mul_f32 v[56:57], v[56:57], v[182:183] op_sel_hi:[1,0]
	v_pk_mul_f32 v[54:55], v[54:55], v[182:183] op_sel_hi:[1,0]
	v_pk_mul_f32 v[52:53], v[52:53], v[182:183] op_sel_hi:[1,0]
	v_pk_mul_f32 v[50:51], v[50:51], v[182:183] op_sel_hi:[1,0]
	v_pk_mul_f32 v[48:49], v[48:49], v[182:183] op_sel_hi:[1,0]
	v_pk_mul_f32 v[46:47], v[46:47], v[182:183] op_sel_hi:[1,0]
	v_pk_mul_f32 v[44:45], v[44:45], v[182:183] op_sel_hi:[1,0]
	v_pk_mul_f32 v[42:43], v[42:43], v[182:183] op_sel_hi:[1,0]
	v_pk_mul_f32 v[40:41], v[40:41], v[182:183] op_sel_hi:[1,0]
	v_pk_mul_f32 v[38:39], v[38:39], v[182:183] op_sel_hi:[1,0]
	v_pk_mul_f32 v[36:37], v[36:37], v[182:183] op_sel_hi:[1,0]
	v_pk_mul_f32 v[34:35], v[34:35], v[182:183] op_sel_hi:[1,0]
	v_pk_mul_f32 v[32:33], v[32:33], v[182:183] op_sel_hi:[1,0]
	v_pk_mul_f32 v[30:31], v[30:31], v[182:183] op_sel_hi:[1,0]
	v_pk_mul_f32 v[28:29], v[28:29], v[182:183] op_sel_hi:[1,0]
	v_pk_mul_f32 v[26:27], v[26:27], v[182:183] op_sel_hi:[1,0]
	v_pk_mul_f32 v[24:25], v[24:25], v[182:183] op_sel_hi:[1,0]
	v_pk_mul_f32 v[22:23], v[22:23], v[182:183] op_sel_hi:[1,0]
	v_pk_mul_f32 v[20:21], v[20:21], v[182:183] op_sel_hi:[1,0]
	v_pk_mul_f32 v[18:19], v[18:19], v[182:183] op_sel_hi:[1,0]
	v_pk_mul_f32 v[16:17], v[16:17], v[182:183] op_sel_hi:[1,0]
.LBB0_676:
	v_add_u32_e32 v204, s31, v184
	v_cvt_pk_bf16_f32 v80, v80, v81
	v_cvt_pk_bf16_f32 v81, v82, v83
	v_cvt_pk_bf16_f32 v82, v84, v85
	v_cvt_pk_bf16_f32 v83, v86, v203
	v_cvt_pk_bf16_f32 v84, v87, v88
	v_cvt_pk_bf16_f32 v85, v89, v90
	v_cvt_pk_bf16_f32 v86, v91, v92
	v_cvt_pk_bf16_f32 v87, v93, v94
	v_add_u32_e32 v203, v204, v188
	v_add_u32_e32 v208, v204, v189
	ds_read_b128 v[88:91], v203 offset:0
	ds_read_b128 v[92:95], v203 offset:4096
	ds_read_b128 v[214:217], v203 offset:8192
	ds_read_b128 v[228:231], v203 offset:12288
	ds_read_b128 v[232:235], v208 offset:0
	ds_read_b128 v[236:239], v208 offset:4096
	s_waitcnt lgkmcnt(5)
	v_mfma_f32_32x32x16_bf16 v[64:79], v[88:91], v[80:83], v[64:79]
	ds_read_b128 v[88:91], v208 offset:8192
	s_waitcnt lgkmcnt(5)
	v_mfma_f32_32x32x16_bf16 v[48:63], v[92:95], v[80:83], v[48:63]
	ds_read_b128 v[92:95], v208 offset:12288
	s_waitcnt lgkmcnt(5)
	v_mfma_f32_32x32x16_bf16 v[32:47], v[214:217], v[80:83], v[32:47]
	s_waitcnt lgkmcnt(4)
	v_mfma_f32_32x32x16_bf16 v[16:31], v[228:231], v[80:83], v[16:31]
	s_waitcnt lgkmcnt(3)
	v_mfma_f32_32x32x16_bf16 v[64:79], v[232:235], v[84:87], v[64:79]
	s_waitcnt lgkmcnt(2)
	v_mfma_f32_32x32x16_bf16 v[48:63], v[236:239], v[84:87], v[48:63]
	s_waitcnt lgkmcnt(1)
	v_mfma_f32_32x32x16_bf16 v[32:47], v[88:91], v[84:87], v[32:47]
	s_waitcnt lgkmcnt(0)
	v_mfma_f32_32x32x16_bf16 v[16:31], v[92:95], v[84:87], v[16:31]
	s_nop 15
	s_nop 3

	v_add_u32_e32 v80, s31, v194
	v_add_u32_e32 v203, v80, v195
	v_add_u32_e32 v208, v80, v196
	v_add_u32_e32 v209, v80, v197
	v_add_u32_e32 v210, v80, v198
	ds_read_b128 v[2:5], v203 offset:0
	ds_read_b128 v[6:9], v208 offset:0
	ds_read_b128 v[10:13], v209 offset:0
	ds_read_b128 v[214:217], v210 offset:0
	ds_read_b128 v[228:231], v203 offset:128
	ds_read_b128 v[232:235], v208 offset:128
	s_waitcnt lgkmcnt(5)
	v_mfma_f32_32x32x16_bf16 v[80:95], v[2:5], v[96:99], 0
	ds_read_b128 v[2:5], v209 offset:128
	s_waitcnt lgkmcnt(5)
	v_mfma_f32_32x32x16_bf16 v[80:95], v[6:9], v[100:103], v[80:95]
	ds_read_b128 v[6:9], v210 offset:128
	s_waitcnt lgkmcnt(5)
	v_mfma_f32_32x32x16_bf16 v[80:95], v[10:13], v[104:107], v[80:95]
	ds_read_b128 v[10:13], v203 offset:256
	s_waitcnt lgkmcnt(5)
	v_mfma_f32_32x32x16_bf16 v[80:95], v[214:217], v[108:111], v[80:95]
	ds_read_b128 v[214:217], v208 offset:256
	s_waitcnt lgkmcnt(5)
	v_mfma_f32_32x32x16_bf16 v[80:95], v[228:231], v[112:115], v[80:95]
	ds_read_b128 v[228:231], v209 offset:256
	s_waitcnt lgkmcnt(5)
	v_mfma_f32_32x32x16_bf16 v[80:95], v[232:235], v[116:119], v[80:95]
	ds_read_b128 v[232:235], v210 offset:256
	s_waitcnt lgkmcnt(5)
	v_mfma_f32_32x32x16_bf16 v[80:95], v[2:5], v[120:123], v[80:95]
	s_waitcnt lgkmcnt(4)
	v_mfma_f32_32x32x16_bf16 v[80:95], v[6:9], v[124:127], v[80:95]
	s_waitcnt lgkmcnt(3)
	v_mfma_f32_32x32x16_bf16 v[80:95], v[10:13], v[128:131], v[80:95]
	s_waitcnt lgkmcnt(2)
	v_mfma_f32_32x32x16_bf16 v[80:95], v[214:217], v[132:135], v[80:95]
	s_waitcnt lgkmcnt(1)
	v_mfma_f32_32x32x16_bf16 v[80:95], v[228:231], v[136:139], v[80:95]
	s_waitcnt lgkmcnt(0)
	v_mfma_f32_32x32x16_bf16 v[80:95], v[232:235], v[140:143], v[80:95]
	s_nop 15
	s_nop 3

	s_nop 0
	v_max3_f32 v0, v80, v81, s4
	v_max3_f32 v2, v82, v83, v84
	v_max3_f32 v3, v85, v86, v87
	v_max3_f32 v0, v0, v88, v89
	v_max3_f32 v2, v2, v90, v91
	v_max3_f32 v3, v3, v92, v93
	v_max3_f32 v0, v0, v94, v95
	v_max3_f32 v0, v0, v2, v3
	v_mov_b32_e32 v2, v0
	s_nop 1
	v_permlane32_swap_b32_e32 v0, v2
	v_max3_f32 v203, v205, v0, v2
	v_mul_f32_e32 v0, 0xbdd53b94, v203
	v_sub_f32_e32 v2, v205, v203
	v_mul_f32_e32 v3, 0x3dd53b94, v2
	v_fmamk_f32 v2, v80, 0x3dd53b94, v0
	v_exp_f32_e32 v4, v2
	v_fmamk_f32 v2, v81, 0x3dd53b94, v0
	v_exp_f32_e32 v5, v2
	v_fmamk_f32 v2, v82, 0x3dd53b94, v0
	v_exp_f32_e32 v6, v2
	v_fmamk_f32 v2, v83, 0x3dd53b94, v0
	v_exp_f32_e32 v7, v2
	v_fmamk_f32 v8, v84, 0x3dd53b94, v0
	v_add_f32_e32 v2, 0, v4
	v_exp_f32_e32 v8, v8
	v_fmamk_f32 v9, v85, 0x3dd53b94, v0
	v_add_f32_e32 v2, v5, v2
	v_exp_f32_e32 v9, v9
	v_fmamk_f32 v10, v86, 0x3dd53b94, v0
	v_add_f32_e32 v2, v6, v2
	v_exp_f32_e32 v10, v10
	v_fmamk_f32 v11, v87, 0x3dd53b94, v0
	v_add_f32_e32 v2, v7, v2
	v_exp_f32_e32 v12, v11
	v_fmamk_f32 v11, v88, 0x3dd53b94, v0
	v_add_f32_e32 v2, v8, v2
	v_exp_f32_e32 v11, v11
	v_fmamk_f32 v13, v89, 0x3dd53b94, v0
	v_add_f32_e32 v2, v9, v2
	v_exp_f32_e32 v13, v13
	v_fmamk_f32 v14, v90, 0x3dd53b94, v0
	v_add_f32_e32 v2, v10, v2
	v_exp_f32_e32 v14, v14
	v_fmamk_f32 v15, v91, 0x3dd53b94, v0
	v_add_f32_e32 v2, v12, v2
	v_exp_f32_e32 v15, v15
	v_fmamk_f32 v80, v92, 0x3dd53b94, v0
	v_add_f32_e32 v2, v11, v2
	v_exp_f32_e32 v80, v80
	v_fmamk_f32 v81, v93, 0x3dd53b94, v0
	v_add_f32_e32 v2, v13, v2
	v_exp_f32_e32 v81, v81
	v_fmamk_f32 v82, v94, 0x3dd53b94, v0
	v_add_f32_e32 v2, v14, v2
	v_exp_f32_e32 v82, v82
	v_fmac_f32_e32 v0, 0x3dd53b94, v95
	v_add_f32_e32 v2, v15, v2
	v_exp_f32_e32 v83, v0
	v_add_f32_e32 v0, v80, v2
	v_add_f32_e32 v0, v81, v0
	v_add_f32_e32 v0, v82, v0
	v_add_f32_e32 v2, v83, v0
	v_exp_f32_e32 v0, v3
	v_mov_b32_e32 v3, v2
	s_nop 1
	v_permlane32_swap_b32_e32 v2, v3
	v_cmp_neq_f32_e32 vcc, 1.0, v0
	s_cbranch_vccz .LBB0_678
	v_pk_mul_f32 v[78:79], v[78:79], v[0:1] op_sel_hi:[1,0]
	v_pk_mul_f32 v[76:77], v[76:77], v[0:1] op_sel_hi:[1,0]
	v_pk_mul_f32 v[74:75], v[74:75], v[0:1] op_sel_hi:[1,0]
	v_pk_mul_f32 v[72:73], v[72:73], v[0:1] op_sel_hi:[1,0]
	v_pk_mul_f32 v[70:71], v[70:71], v[0:1] op_sel_hi:[1,0]
	v_pk_mul_f32 v[68:69], v[68:69], v[0:1] op_sel_hi:[1,0]
	v_pk_mul_f32 v[66:67], v[66:67], v[0:1] op_sel_hi:[1,0]
	v_pk_mul_f32 v[64:65], v[64:65], v[0:1] op_sel_hi:[1,0]
	v_pk_mul_f32 v[62:63], v[62:63], v[0:1] op_sel_hi:[1,0]
	v_pk_mul_f32 v[60:61], v[60:61], v[0:1] op_sel_hi:[1,0]
	v_pk_mul_f32 v[58:59], v[58:59], v[0:1] op_sel_hi:[1,0]
	v_pk_mul_f32 v[56:57], v[56:57], v[0:1] op_sel_hi:[1,0]
	v_pk_mul_f32 v[54:55], v[54:55], v[0:1] op_sel_hi:[1,0]
	v_pk_mul_f32 v[52:53], v[52:53], v[0:1] op_sel_hi:[1,0]
	v_pk_mul_f32 v[50:51], v[50:51], v[0:1] op_sel_hi:[1,0]
	v_pk_mul_f32 v[48:49], v[48:49], v[0:1] op_sel_hi:[1,0]
	v_pk_mul_f32 v[46:47], v[46:47], v[0:1] op_sel_hi:[1,0]
	v_pk_mul_f32 v[44:45], v[44:45], v[0:1] op_sel_hi:[1,0]
	v_pk_mul_f32 v[42:43], v[42:43], v[0:1] op_sel_hi:[1,0]
	v_pk_mul_f32 v[40:41], v[40:41], v[0:1] op_sel_hi:[1,0]
	v_pk_mul_f32 v[38:39], v[38:39], v[0:1] op_sel_hi:[1,0]
	v_pk_mul_f32 v[36:37], v[36:37], v[0:1] op_sel_hi:[1,0]
	v_pk_mul_f32 v[34:35], v[34:35], v[0:1] op_sel_hi:[1,0]
	v_pk_mul_f32 v[32:33], v[32:33], v[0:1] op_sel_hi:[1,0]
	v_pk_mul_f32 v[30:31], v[30:31], v[0:1] op_sel_hi:[1,0]
	v_pk_mul_f32 v[28:29], v[28:29], v[0:1] op_sel_hi:[1,0]
	v_pk_mul_f32 v[26:27], v[26:27], v[0:1] op_sel_hi:[1,0]
	v_pk_mul_f32 v[24:25], v[24:25], v[0:1] op_sel_hi:[1,0]
	v_pk_mul_f32 v[22:23], v[22:23], v[0:1] op_sel_hi:[1,0]
	v_pk_mul_f32 v[20:21], v[20:21], v[0:1] op_sel_hi:[1,0]
	v_pk_mul_f32 v[18:19], v[18:19], v[0:1] op_sel_hi:[1,0]
	v_pk_mul_f32 v[16:17], v[16:17], v[0:1] op_sel_hi:[1,0]
